# norm phases rewritten by hand: 3 rows per iteration per wave (no latency-bound 9th-row tail), gain vectors preloaded into registers, scalar row logic; same arithmetic order
# speedup vs baseline: 1.0364x; 1.0216x over previous
.LBB0_1221:
	s_or_b64 exec, exec, s[12:13]
	s_waitcnt lgkmcnt(0)
	v_mov_b32_e32 v0, v136
	s_barrier
	s_nop 0
	v_lshrrev_b32_e32 v104, 6, v136
	v_and_b32_e32 v105, 63, v136
	v_readfirstlane_b32 s36, v104
	v_lshlrev_b32_e32 v106, 4, v105
	v_lshlrev_b32_e32 v107, 3, v105
	s_add_i32 s36, s82, s36
	s_cmpk_lt_i32 s36, 0x4100
	s_cbranch_scc0 .LnrmA_done
	v_xor_b32_e32 v108, 32, v105
	v_xor_b32_e32 v109, 16, v105
	v_xor_b32_e32 v110, 8, v105
	v_xor_b32_e32 v111, 4, v105
	v_xor_b32_e32 v112, 2, v105
	v_xor_b32_e32 v113, 1, v105
	v_lshlrev_b32_e32 v108, 2, v108
	v_lshlrev_b32_e32 v109, 2, v109
	v_lshlrev_b32_e32 v110, 2, v110
	v_lshlrev_b32_e32 v111, 2, v111
	v_lshlrev_b32_e32 v112, 2, v112
	v_lshlrev_b32_e32 v113, 2, v113
	v_readlane_b32 s42, v252, 46
	v_readlane_b32 s0, v249, 58
	v_readlane_b32 s1, v249, 59
	v_readlane_b32 s12, v249, 56
	v_readlane_b32 s13, v249, 57
	v_readlane_b32 s40, v252, 44
	v_readlane_b32 s41, v252, 45
	s_nop 4
	global_load_dwordx4 v[72:75], v106, s[0:1]
	global_load_dwordx4 v[76:79], v106, s[0:1] offset:1024
	global_load_dwordx4 v[80:83], v106, s[0:1] offset:2048
	global_load_dwordx4 v[84:87], v106, s[0:1] offset:3072
	s_cmp_eq_u32 s42, 0
	s_cbranch_scc1 .LnrmA_loop
	global_load_dwordx4 v[88:91], v106, s[12:13]
	global_load_dwordx4 v[92:95], v106, s[12:13] offset:1024
	global_load_dwordx4 v[96:99], v106, s[12:13] offset:2048
	global_load_dwordx4 v[100:103], v106, s[12:13] offset:3072
.LnrmA_loop:
	s_mov_b32 s37, s36
	s_cmpk_gt_i32 s37, 0x207f
	s_cselect_b32 s43, 0x2080, 0
	s_cselect_b32 vcc_lo, 0x2000, 0
	s_cselect_b32 vcc_hi, 0x80, 0
	s_sub_i32 s43, s37, s43
	s_add_i32 vcc_lo, vcc_lo, s43
	s_addk_i32 vcc_lo, 0xff80
	s_add_i32 vcc_hi, vcc_hi, s43
	s_cmpk_lt_i32 s43, 0x80
	s_cselect_b32 vcc_lo, vcc_hi, vcc_lo
	s_cselect_b32 s0, s40, s92
	s_cselect_b32 s1, s41, s93
	s_lshl_b32 vcc_lo, vcc_lo, 12
	s_lshl_b32 vcc_hi, s37, 11
	v_add_u32_e32 v114, vcc_lo, v106
	v_add_u32_e32 v117, vcc_hi, v107
	global_load_dwordx2 v[16:17], v117, s[4:5] nt
	global_load_dwordx2 v[18:19], v117, s[4:5] offset:512 nt
	global_load_dwordx2 v[20:21], v117, s[4:5] offset:1024 nt
	global_load_dwordx2 v[22:23], v117, s[4:5] offset:1536 nt
	global_load_dwordx4 v[0:3], v114, s[0:1] nt
	global_load_dwordx4 v[4:7], v114, s[0:1] offset:1024 nt
	global_load_dwordx4 v[8:11], v114, s[0:1] offset:2048 nt
	global_load_dwordx4 v[12:15], v114, s[0:1] offset:3072 nt
	s_add_i32 s37, s36, 2048
	s_cmpk_lt_i32 s37, 0x4100
	s_cselect_b32 s37, s37, s36
	s_cmpk_gt_i32 s37, 0x207f
	s_cselect_b32 s43, 0x2080, 0
	s_cselect_b32 vcc_lo, 0x2000, 0
	s_cselect_b32 vcc_hi, 0x80, 0
	s_sub_i32 s43, s37, s43
	s_add_i32 vcc_lo, vcc_lo, s43
	s_addk_i32 vcc_lo, 0xff80
	s_add_i32 vcc_hi, vcc_hi, s43
	s_cmpk_lt_i32 s43, 0x80
	s_cselect_b32 vcc_lo, vcc_hi, vcc_lo
	s_cselect_b32 s12, s40, s92
	s_cselect_b32 s13, s41, s93
	s_lshl_b32 vcc_lo, vcc_lo, 12
	s_lshl_b32 vcc_hi, s37, 11
	v_add_u32_e32 v115, vcc_lo, v106
	v_add_u32_e32 v118, vcc_hi, v107
	global_load_dwordx2 v[40:41], v118, s[4:5] nt
	global_load_dwordx2 v[42:43], v118, s[4:5] offset:512 nt
	global_load_dwordx2 v[44:45], v118, s[4:5] offset:1024 nt
	global_load_dwordx2 v[46:47], v118, s[4:5] offset:1536 nt
	global_load_dwordx4 v[24:27], v115, s[12:13] nt
	global_load_dwordx4 v[28:31], v115, s[12:13] offset:1024 nt
	global_load_dwordx4 v[32:35], v115, s[12:13] offset:2048 nt
	global_load_dwordx4 v[36:39], v115, s[12:13] offset:3072 nt
	s_add_i32 s37, s36, 4096
	s_cmpk_lt_i32 s37, 0x4100
	s_cselect_b32 s37, s37, s36
	s_cmpk_gt_i32 s37, 0x207f
	s_cselect_b32 s43, 0x2080, 0
	s_cselect_b32 vcc_lo, 0x2000, 0
	s_cselect_b32 vcc_hi, 0x80, 0
	s_sub_i32 s43, s37, s43
	s_add_i32 vcc_lo, vcc_lo, s43
	s_addk_i32 vcc_lo, 0xff80
	s_add_i32 vcc_hi, vcc_hi, s43
	s_cmpk_lt_i32 s43, 0x80
	s_cselect_b32 vcc_lo, vcc_hi, vcc_lo
	s_cselect_b32 s38, s40, s92
	s_cselect_b32 s39, s41, s93
	s_lshl_b32 vcc_lo, vcc_lo, 12
	s_lshl_b32 vcc_hi, s37, 11
	v_add_u32_e32 v116, vcc_lo, v106
	v_add_u32_e32 v119, vcc_hi, v107
	global_load_dwordx2 v[64:65], v119, s[4:5] nt
	global_load_dwordx2 v[66:67], v119, s[4:5] offset:512 nt
	global_load_dwordx2 v[68:69], v119, s[4:5] offset:1024 nt
	global_load_dwordx2 v[70:71], v119, s[4:5] offset:1536 nt
	global_load_dwordx4 v[48:51], v116, s[38:39] nt
	global_load_dwordx4 v[52:55], v116, s[38:39] offset:1024 nt
	global_load_dwordx4 v[56:59], v116, s[38:39] offset:2048 nt
	global_load_dwordx4 v[60:63], v116, s[38:39] offset:3072 nt
	s_waitcnt vmcnt(16)
	v_lshlrev_b32_e32 v120, 16, v16
	v_and_b32_e32 v16, 0xffff0000, v16
	v_lshlrev_b32_e32 v121, 16, v17
	v_and_b32_e32 v17, 0xffff0000, v17
	v_lshlrev_b32_e32 v122, 16, v18
	v_and_b32_e32 v18, 0xffff0000, v18
	v_lshlrev_b32_e32 v123, 16, v19
	v_and_b32_e32 v19, 0xffff0000, v19
	v_lshlrev_b32_e32 v124, 16, v20
	v_and_b32_e32 v20, 0xffff0000, v20
	v_lshlrev_b32_e32 v125, 16, v21
	v_and_b32_e32 v21, 0xffff0000, v21
	v_lshlrev_b32_e32 v126, 16, v22
	v_and_b32_e32 v22, 0xffff0000, v22
	v_lshlrev_b32_e32 v127, 16, v23
	v_and_b32_e32 v23, 0xffff0000, v23
	v_mul_f32_e32 v128, v16, v16
	v_mul_f32_e32 v129, v18, v18
	v_mul_f32_e32 v130, v20, v20
	v_mul_f32_e32 v131, v22, v22
	v_fmac_f32_e32 v128, v120, v120
	v_fmac_f32_e32 v129, v122, v122
	v_fmac_f32_e32 v130, v124, v124
	v_fmac_f32_e32 v131, v126, v126
	v_fmac_f32_e32 v128, v121, v121
	v_fmac_f32_e32 v129, v123, v123
	v_fmac_f32_e32 v130, v125, v125
	v_fmac_f32_e32 v131, v127, v127
	v_fmac_f32_e32 v128, v17, v17
	v_fmac_f32_e32 v129, v19, v19
	v_fmac_f32_e32 v130, v21, v21
	v_fmac_f32_e32 v131, v23, v23
	v_add_f32_e32 v132, v128, v129
	v_add_f32_e32 v132, v132, v130
	v_add_f32_e32 v132, v132, v131
	ds_bpermute_b32 v138, v108, v132
	s_waitcnt lgkmcnt(0)
	v_add_f32_e32 v132, v132, v138
	ds_bpermute_b32 v138, v109, v132
	s_waitcnt lgkmcnt(0)
	v_add_f32_e32 v132, v132, v138
	ds_bpermute_b32 v138, v110, v132
	s_waitcnt lgkmcnt(0)
	v_add_f32_e32 v132, v132, v138
	ds_bpermute_b32 v138, v111, v132
	s_waitcnt lgkmcnt(0)
	v_add_f32_e32 v132, v132, v138
	ds_bpermute_b32 v138, v112, v132
	s_waitcnt lgkmcnt(0)
	v_add_f32_e32 v132, v132, v138
	ds_bpermute_b32 v138, v113, v132
	s_waitcnt lgkmcnt(0)
	v_add_f32_e32 v132, v132, v138
	v_fmamk_f32 v132, v132, 0x3a800000, v177
	v_mov_b32_e32 v135, 0x800000
	v_cmp_gt_f32_e32 vcc, v135, v132
	v_mul_f32_e32 v133, 0x4b800000, v132
	s_nop 1
	v_cndmask_b32_e32 v132, v132, v133, vcc
	v_rsq_f32_e32 v132, v132
	s_nop 0
	v_mul_f32_e32 v133, 0x45800000, v132
	v_cndmask_b32_e32 v134, v132, v133, vcc
	v_mul_f32_e32 v120, v72, v120
	v_mul_f32_e32 v16, v73, v16
	v_mul_f32_e32 v121, v74, v121
	v_mul_f32_e32 v17, v75, v17
	v_mul_f32_e32 v122, v76, v122
	v_mul_f32_e32 v18, v77, v18
	v_mul_f32_e32 v123, v78, v123
	v_mul_f32_e32 v19, v79, v19
	v_mul_f32_e32 v124, v80, v124
	v_mul_f32_e32 v20, v81, v20
	v_mul_f32_e32 v125, v82, v125
	v_mul_f32_e32 v21, v83, v21
	v_mul_f32_e32 v126, v84, v126
	v_mul_f32_e32 v22, v85, v22
	v_mul_f32_e32 v127, v86, v127
	v_mul_f32_e32 v23, v87, v23
	v_fmac_f32_e32 v0, v120, v134
	v_fmac_f32_e32 v1, v16, v134
	v_fmac_f32_e32 v2, v121, v134
	v_fmac_f32_e32 v3, v17, v134
	v_fmac_f32_e32 v4, v122, v134
	v_fmac_f32_e32 v5, v18, v134
	v_fmac_f32_e32 v6, v123, v134
	v_fmac_f32_e32 v7, v19, v134
	v_fmac_f32_e32 v8, v124, v134
	v_fmac_f32_e32 v9, v20, v134
	v_fmac_f32_e32 v10, v125, v134
	v_fmac_f32_e32 v11, v21, v134
	v_fmac_f32_e32 v12, v126, v134
	v_fmac_f32_e32 v13, v22, v134
	v_fmac_f32_e32 v14, v127, v134
	v_fmac_f32_e32 v15, v23, v134
	global_store_dwordx4 v114, v[0:3], s[0:1] nt
	global_store_dwordx4 v114, v[4:7], s[0:1] offset:1024 nt
	global_store_dwordx4 v114, v[8:11], s[0:1] offset:2048 nt
	global_store_dwordx4 v114, v[12:15], s[0:1] offset:3072 nt
	s_cmp_eq_u32 s42, 0
	s_cbranch_scc1 .LnrmA_nopre0
	v_mul_f32_e32 v128, v1, v1
	v_mul_f32_e32 v129, v5, v5
	v_mul_f32_e32 v130, v9, v9
	v_mul_f32_e32 v131, v13, v13
	v_fmac_f32_e32 v128, v0, v0
	v_fmac_f32_e32 v129, v4, v4
	v_fmac_f32_e32 v130, v8, v8
	v_fmac_f32_e32 v131, v12, v12
	v_fmac_f32_e32 v128, v2, v2
	v_fmac_f32_e32 v129, v6, v6
	v_fmac_f32_e32 v130, v10, v10
	v_fmac_f32_e32 v131, v14, v14
	v_fmac_f32_e32 v128, v3, v3
	v_fmac_f32_e32 v129, v7, v7
	v_fmac_f32_e32 v130, v11, v11
	v_fmac_f32_e32 v131, v15, v15
	v_add_f32_e32 v132, v128, v129
	v_add_f32_e32 v132, v130, v132
	v_add_f32_e32 v132, v131, v132
	ds_bpermute_b32 v138, v108, v132
	s_waitcnt lgkmcnt(0)
	v_add_f32_e32 v132, v132, v138
	ds_bpermute_b32 v138, v109, v132
	s_waitcnt lgkmcnt(0)
	v_add_f32_e32 v132, v132, v138
	ds_bpermute_b32 v138, v110, v132
	s_waitcnt lgkmcnt(0)
	v_add_f32_e32 v132, v132, v138
	ds_bpermute_b32 v138, v111, v132
	s_waitcnt lgkmcnt(0)
	v_add_f32_e32 v132, v132, v138
	ds_bpermute_b32 v138, v112, v132
	s_waitcnt lgkmcnt(0)
	v_add_f32_e32 v132, v132, v138
	ds_bpermute_b32 v138, v113, v132
	s_waitcnt lgkmcnt(0)
	v_add_f32_e32 v132, v132, v138
	v_fmamk_f32 v132, v132, 0x3a800000, v177
	v_mov_b32_e32 v135, 0x800000
	v_cmp_gt_f32_e32 vcc, v135, v132
	v_mul_f32_e32 v133, 0x4b800000, v132
	s_nop 1
	v_cndmask_b32_e32 v132, v132, v133, vcc
	v_rsq_f32_e32 v132, v132
	s_nop 0
	v_mul_f32_e32 v133, 0x45800000, v132
	v_cndmask_b32_e32 v134, v132, v133, vcc
	v_mul_f32_e32 v0, v0, v88
	v_mul_f32_e32 v1, v1, v89
	v_mul_f32_e32 v2, v2, v90
	v_mul_f32_e32 v3, v3, v91
	v_mul_f32_e32 v4, v4, v92
	v_mul_f32_e32 v5, v5, v93
	v_mul_f32_e32 v6, v6, v94
	v_mul_f32_e32 v7, v7, v95
	v_mul_f32_e32 v8, v8, v96
	v_mul_f32_e32 v9, v9, v97
	v_mul_f32_e32 v10, v10, v98
	v_mul_f32_e32 v11, v11, v99
	v_mul_f32_e32 v12, v12, v100
	v_mul_f32_e32 v13, v13, v101
	v_mul_f32_e32 v14, v14, v102
	v_mul_f32_e32 v15, v15, v103
	v_mul_f32_e32 v0, v0, v134
	v_mul_f32_e32 v1, v1, v134
	v_mul_f32_e32 v2, v2, v134
	v_mul_f32_e32 v3, v3, v134
	v_mul_f32_e32 v4, v4, v134
	v_mul_f32_e32 v5, v5, v134
	v_mul_f32_e32 v6, v6, v134
	v_mul_f32_e32 v7, v7, v134
	v_mul_f32_e32 v8, v8, v134
	v_mul_f32_e32 v9, v9, v134
	v_mul_f32_e32 v10, v10, v134
	v_mul_f32_e32 v11, v11, v134
	v_mul_f32_e32 v12, v12, v134
	v_mul_f32_e32 v13, v13, v134
	v_mul_f32_e32 v14, v14, v134
	v_mul_f32_e32 v15, v15, v134
	v_cvt_pk_bf16_f32 v120, v0, v1
	v_cvt_pk_bf16_f32 v121, v2, v3
	v_cvt_pk_bf16_f32 v122, v4, v5
	v_cvt_pk_bf16_f32 v123, v6, v7
	v_cvt_pk_bf16_f32 v124, v8, v9
	v_cvt_pk_bf16_f32 v125, v10, v11
	v_cvt_pk_bf16_f32 v126, v12, v13
	v_cvt_pk_bf16_f32 v127, v14, v15
	global_store_dwordx2 v117, v[120:121], s[4:5] nt
	global_store_dwordx2 v117, v[122:123], s[4:5] offset:512 nt
	global_store_dwordx2 v117, v[124:125], s[4:5] offset:1024 nt
	global_store_dwordx2 v117, v[126:127], s[4:5] offset:1536 nt
.LnrmA_nopre0:
	s_add_i32 s37, s36, 2048
	s_cmpk_lt_i32 s37, 0x4100
	s_cbranch_scc0 .LnrmA_skip1
	s_waitcnt vmcnt(12)
	v_lshlrev_b32_e32 v120, 16, v40
	v_and_b32_e32 v40, 0xffff0000, v40
	v_lshlrev_b32_e32 v121, 16, v41
	v_and_b32_e32 v41, 0xffff0000, v41
	v_lshlrev_b32_e32 v122, 16, v42
	v_and_b32_e32 v42, 0xffff0000, v42
	v_lshlrev_b32_e32 v123, 16, v43
	v_and_b32_e32 v43, 0xffff0000, v43
	v_lshlrev_b32_e32 v124, 16, v44
	v_and_b32_e32 v44, 0xffff0000, v44
	v_lshlrev_b32_e32 v125, 16, v45
	v_and_b32_e32 v45, 0xffff0000, v45
	v_lshlrev_b32_e32 v126, 16, v46
	v_and_b32_e32 v46, 0xffff0000, v46
	v_lshlrev_b32_e32 v127, 16, v47
	v_and_b32_e32 v47, 0xffff0000, v47
	v_mul_f32_e32 v128, v40, v40
	v_mul_f32_e32 v129, v42, v42
	v_mul_f32_e32 v130, v44, v44
	v_mul_f32_e32 v131, v46, v46
	v_fmac_f32_e32 v128, v120, v120
	v_fmac_f32_e32 v129, v122, v122
	v_fmac_f32_e32 v130, v124, v124
	v_fmac_f32_e32 v131, v126, v126
	v_fmac_f32_e32 v128, v121, v121
	v_fmac_f32_e32 v129, v123, v123
	v_fmac_f32_e32 v130, v125, v125
	v_fmac_f32_e32 v131, v127, v127
	v_fmac_f32_e32 v128, v41, v41
	v_fmac_f32_e32 v129, v43, v43
	v_fmac_f32_e32 v130, v45, v45
	v_fmac_f32_e32 v131, v47, v47
	v_add_f32_e32 v132, v128, v129
	v_add_f32_e32 v132, v132, v130
	v_add_f32_e32 v132, v132, v131
	ds_bpermute_b32 v138, v108, v132
	s_waitcnt lgkmcnt(0)
	v_add_f32_e32 v132, v132, v138
	ds_bpermute_b32 v138, v109, v132
	s_waitcnt lgkmcnt(0)
	v_add_f32_e32 v132, v132, v138
	ds_bpermute_b32 v138, v110, v132
	s_waitcnt lgkmcnt(0)
	v_add_f32_e32 v132, v132, v138
	ds_bpermute_b32 v138, v111, v132
	s_waitcnt lgkmcnt(0)
	v_add_f32_e32 v132, v132, v138
	ds_bpermute_b32 v138, v112, v132
	s_waitcnt lgkmcnt(0)
	v_add_f32_e32 v132, v132, v138
	ds_bpermute_b32 v138, v113, v132
	s_waitcnt lgkmcnt(0)
	v_add_f32_e32 v132, v132, v138
	v_fmamk_f32 v132, v132, 0x3a800000, v177
	v_mov_b32_e32 v135, 0x800000
	v_cmp_gt_f32_e32 vcc, v135, v132
	v_mul_f32_e32 v133, 0x4b800000, v132
	s_nop 1
	v_cndmask_b32_e32 v132, v132, v133, vcc
	v_rsq_f32_e32 v132, v132
	s_nop 0
	v_mul_f32_e32 v133, 0x45800000, v132
	v_cndmask_b32_e32 v134, v132, v133, vcc
	v_mul_f32_e32 v120, v72, v120
	v_mul_f32_e32 v40, v73, v40
	v_mul_f32_e32 v121, v74, v121
	v_mul_f32_e32 v41, v75, v41
	v_mul_f32_e32 v122, v76, v122
	v_mul_f32_e32 v42, v77, v42
	v_mul_f32_e32 v123, v78, v123
	v_mul_f32_e32 v43, v79, v43
	v_mul_f32_e32 v124, v80, v124
	v_mul_f32_e32 v44, v81, v44
	v_mul_f32_e32 v125, v82, v125
	v_mul_f32_e32 v45, v83, v45
	v_mul_f32_e32 v126, v84, v126
	v_mul_f32_e32 v46, v85, v46
	v_mul_f32_e32 v127, v86, v127
	v_mul_f32_e32 v47, v87, v47
	v_fmac_f32_e32 v24, v120, v134
	v_fmac_f32_e32 v25, v40, v134
	v_fmac_f32_e32 v26, v121, v134
	v_fmac_f32_e32 v27, v41, v134
	v_fmac_f32_e32 v28, v122, v134
	v_fmac_f32_e32 v29, v42, v134
	v_fmac_f32_e32 v30, v123, v134
	v_fmac_f32_e32 v31, v43, v134
	v_fmac_f32_e32 v32, v124, v134
	v_fmac_f32_e32 v33, v44, v134
	v_fmac_f32_e32 v34, v125, v134
	v_fmac_f32_e32 v35, v45, v134
	v_fmac_f32_e32 v36, v126, v134
	v_fmac_f32_e32 v37, v46, v134
	v_fmac_f32_e32 v38, v127, v134
	v_fmac_f32_e32 v39, v47, v134
	global_store_dwordx4 v115, v[24:27], s[12:13] nt
	global_store_dwordx4 v115, v[28:31], s[12:13] offset:1024 nt
	global_store_dwordx4 v115, v[32:35], s[12:13] offset:2048 nt
	global_store_dwordx4 v115, v[36:39], s[12:13] offset:3072 nt
	s_cmp_eq_u32 s42, 0
	s_cbranch_scc1 .LnrmA_skip1
	v_mul_f32_e32 v128, v25, v25
	v_mul_f32_e32 v129, v29, v29
	v_mul_f32_e32 v130, v33, v33
	v_mul_f32_e32 v131, v37, v37
	v_fmac_f32_e32 v128, v24, v24
	v_fmac_f32_e32 v129, v28, v28
	v_fmac_f32_e32 v130, v32, v32
	v_fmac_f32_e32 v131, v36, v36
	v_fmac_f32_e32 v128, v26, v26
	v_fmac_f32_e32 v129, v30, v30
	v_fmac_f32_e32 v130, v34, v34
	v_fmac_f32_e32 v131, v38, v38
	v_fmac_f32_e32 v128, v27, v27
	v_fmac_f32_e32 v129, v31, v31
	v_fmac_f32_e32 v130, v35, v35
	v_fmac_f32_e32 v131, v39, v39
	v_add_f32_e32 v132, v128, v129
	v_add_f32_e32 v132, v130, v132
	v_add_f32_e32 v132, v131, v132
	ds_bpermute_b32 v138, v108, v132
	s_waitcnt lgkmcnt(0)
	v_add_f32_e32 v132, v132, v138
	ds_bpermute_b32 v138, v109, v132
	s_waitcnt lgkmcnt(0)
	v_add_f32_e32 v132, v132, v138
	ds_bpermute_b32 v138, v110, v132
	s_waitcnt lgkmcnt(0)
	v_add_f32_e32 v132, v132, v138
	ds_bpermute_b32 v138, v111, v132
	s_waitcnt lgkmcnt(0)
	v_add_f32_e32 v132, v132, v138
	ds_bpermute_b32 v138, v112, v132
	s_waitcnt lgkmcnt(0)
	v_add_f32_e32 v132, v132, v138
	ds_bpermute_b32 v138, v113, v132
	s_waitcnt lgkmcnt(0)
	v_add_f32_e32 v132, v132, v138
	v_fmamk_f32 v132, v132, 0x3a800000, v177
	v_mov_b32_e32 v135, 0x800000
	v_cmp_gt_f32_e32 vcc, v135, v132
	v_mul_f32_e32 v133, 0x4b800000, v132
	s_nop 1
	v_cndmask_b32_e32 v132, v132, v133, vcc
	v_rsq_f32_e32 v132, v132
	s_nop 0
	v_mul_f32_e32 v133, 0x45800000, v132
	v_cndmask_b32_e32 v134, v132, v133, vcc
	v_mul_f32_e32 v24, v24, v88
	v_mul_f32_e32 v25, v25, v89
	v_mul_f32_e32 v26, v26, v90
	v_mul_f32_e32 v27, v27, v91
	v_mul_f32_e32 v28, v28, v92
	v_mul_f32_e32 v29, v29, v93
	v_mul_f32_e32 v30, v30, v94
	v_mul_f32_e32 v31, v31, v95
	v_mul_f32_e32 v32, v32, v96
	v_mul_f32_e32 v33, v33, v97
	v_mul_f32_e32 v34, v34, v98
	v_mul_f32_e32 v35, v35, v99
	v_mul_f32_e32 v36, v36, v100
	v_mul_f32_e32 v37, v37, v101
	v_mul_f32_e32 v38, v38, v102
	v_mul_f32_e32 v39, v39, v103
	v_mul_f32_e32 v24, v24, v134
	v_mul_f32_e32 v25, v25, v134
	v_mul_f32_e32 v26, v26, v134
	v_mul_f32_e32 v27, v27, v134
	v_mul_f32_e32 v28, v28, v134
	v_mul_f32_e32 v29, v29, v134
	v_mul_f32_e32 v30, v30, v134
	v_mul_f32_e32 v31, v31, v134
	v_mul_f32_e32 v32, v32, v134
	v_mul_f32_e32 v33, v33, v134
	v_mul_f32_e32 v34, v34, v134
	v_mul_f32_e32 v35, v35, v134
	v_mul_f32_e32 v36, v36, v134
	v_mul_f32_e32 v37, v37, v134
	v_mul_f32_e32 v38, v38, v134
	v_mul_f32_e32 v39, v39, v134
	v_cvt_pk_bf16_f32 v120, v24, v25
	v_cvt_pk_bf16_f32 v121, v26, v27
	v_cvt_pk_bf16_f32 v122, v28, v29
	v_cvt_pk_bf16_f32 v123, v30, v31
	v_cvt_pk_bf16_f32 v124, v32, v33
	v_cvt_pk_bf16_f32 v125, v34, v35
	v_cvt_pk_bf16_f32 v126, v36, v37
	v_cvt_pk_bf16_f32 v127, v38, v39
	global_store_dwordx2 v118, v[120:121], s[4:5] nt
	global_store_dwordx2 v118, v[122:123], s[4:5] offset:512 nt
	global_store_dwordx2 v118, v[124:125], s[4:5] offset:1024 nt
	global_store_dwordx2 v118, v[126:127], s[4:5] offset:1536 nt
.LnrmA_skip1:
	s_add_i32 s37, s36, 4096
	s_cmpk_lt_i32 s37, 0x4100
	s_cbranch_scc0 .LnrmA_skip2
	s_waitcnt vmcnt(8)
	v_lshlrev_b32_e32 v120, 16, v64
	v_and_b32_e32 v64, 0xffff0000, v64
	v_lshlrev_b32_e32 v121, 16, v65
	v_and_b32_e32 v65, 0xffff0000, v65
	v_lshlrev_b32_e32 v122, 16, v66
	v_and_b32_e32 v66, 0xffff0000, v66
	v_lshlrev_b32_e32 v123, 16, v67
	v_and_b32_e32 v67, 0xffff0000, v67
	v_lshlrev_b32_e32 v124, 16, v68
	v_and_b32_e32 v68, 0xffff0000, v68
	v_lshlrev_b32_e32 v125, 16, v69
	v_and_b32_e32 v69, 0xffff0000, v69
	v_lshlrev_b32_e32 v126, 16, v70
	v_and_b32_e32 v70, 0xffff0000, v70
	v_lshlrev_b32_e32 v127, 16, v71
	v_and_b32_e32 v71, 0xffff0000, v71
	v_mul_f32_e32 v128, v64, v64
	v_mul_f32_e32 v129, v66, v66
	v_mul_f32_e32 v130, v68, v68
	v_mul_f32_e32 v131, v70, v70
	v_fmac_f32_e32 v128, v120, v120
	v_fmac_f32_e32 v129, v122, v122
	v_fmac_f32_e32 v130, v124, v124
	v_fmac_f32_e32 v131, v126, v126
	v_fmac_f32_e32 v128, v121, v121
	v_fmac_f32_e32 v129, v123, v123
	v_fmac_f32_e32 v130, v125, v125
	v_fmac_f32_e32 v131, v127, v127
	v_fmac_f32_e32 v128, v65, v65
	v_fmac_f32_e32 v129, v67, v67
	v_fmac_f32_e32 v130, v69, v69
	v_fmac_f32_e32 v131, v71, v71
	v_add_f32_e32 v132, v128, v129
	v_add_f32_e32 v132, v132, v130
	v_add_f32_e32 v132, v132, v131
	ds_bpermute_b32 v138, v108, v132
	s_waitcnt lgkmcnt(0)
	v_add_f32_e32 v132, v132, v138
	ds_bpermute_b32 v138, v109, v132
	s_waitcnt lgkmcnt(0)
	v_add_f32_e32 v132, v132, v138
	ds_bpermute_b32 v138, v110, v132
	s_waitcnt lgkmcnt(0)
	v_add_f32_e32 v132, v132, v138
	ds_bpermute_b32 v138, v111, v132
	s_waitcnt lgkmcnt(0)
	v_add_f32_e32 v132, v132, v138
	ds_bpermute_b32 v138, v112, v132
	s_waitcnt lgkmcnt(0)
	v_add_f32_e32 v132, v132, v138
	ds_bpermute_b32 v138, v113, v132
	s_waitcnt lgkmcnt(0)
	v_add_f32_e32 v132, v132, v138
	v_fmamk_f32 v132, v132, 0x3a800000, v177
	v_mov_b32_e32 v135, 0x800000
	v_cmp_gt_f32_e32 vcc, v135, v132
	v_mul_f32_e32 v133, 0x4b800000, v132
	s_nop 1
	v_cndmask_b32_e32 v132, v132, v133, vcc
	v_rsq_f32_e32 v132, v132
	s_nop 0
	v_mul_f32_e32 v133, 0x45800000, v132
	v_cndmask_b32_e32 v134, v132, v133, vcc
	v_mul_f32_e32 v120, v72, v120
	v_mul_f32_e32 v64, v73, v64
	v_mul_f32_e32 v121, v74, v121
	v_mul_f32_e32 v65, v75, v65
	v_mul_f32_e32 v122, v76, v122
	v_mul_f32_e32 v66, v77, v66
	v_mul_f32_e32 v123, v78, v123
	v_mul_f32_e32 v67, v79, v67
	v_mul_f32_e32 v124, v80, v124
	v_mul_f32_e32 v68, v81, v68
	v_mul_f32_e32 v125, v82, v125
	v_mul_f32_e32 v69, v83, v69
	v_mul_f32_e32 v126, v84, v126
	v_mul_f32_e32 v70, v85, v70
	v_mul_f32_e32 v127, v86, v127
	v_mul_f32_e32 v71, v87, v71
	v_fmac_f32_e32 v48, v120, v134
	v_fmac_f32_e32 v49, v64, v134
	v_fmac_f32_e32 v50, v121, v134
	v_fmac_f32_e32 v51, v65, v134
	v_fmac_f32_e32 v52, v122, v134
	v_fmac_f32_e32 v53, v66, v134
	v_fmac_f32_e32 v54, v123, v134
	v_fmac_f32_e32 v55, v67, v134
	v_fmac_f32_e32 v56, v124, v134
	v_fmac_f32_e32 v57, v68, v134
	v_fmac_f32_e32 v58, v125, v134
	v_fmac_f32_e32 v59, v69, v134
	v_fmac_f32_e32 v60, v126, v134
	v_fmac_f32_e32 v61, v70, v134
	v_fmac_f32_e32 v62, v127, v134
	v_fmac_f32_e32 v63, v71, v134
	global_store_dwordx4 v116, v[48:51], s[38:39] nt
	global_store_dwordx4 v116, v[52:55], s[38:39] offset:1024 nt
	global_store_dwordx4 v116, v[56:59], s[38:39] offset:2048 nt
	global_store_dwordx4 v116, v[60:63], s[38:39] offset:3072 nt
	s_cmp_eq_u32 s42, 0
	s_cbranch_scc1 .LnrmA_skip2
	v_mul_f32_e32 v128, v49, v49
	v_mul_f32_e32 v129, v53, v53
	v_mul_f32_e32 v130, v57, v57
	v_mul_f32_e32 v131, v61, v61
	v_fmac_f32_e32 v128, v48, v48
	v_fmac_f32_e32 v129, v52, v52
	v_fmac_f32_e32 v130, v56, v56
	v_fmac_f32_e32 v131, v60, v60
	v_fmac_f32_e32 v128, v50, v50
	v_fmac_f32_e32 v129, v54, v54
	v_fmac_f32_e32 v130, v58, v58
	v_fmac_f32_e32 v131, v62, v62
	v_fmac_f32_e32 v128, v51, v51
	v_fmac_f32_e32 v129, v55, v55
	v_fmac_f32_e32 v130, v59, v59
	v_fmac_f32_e32 v131, v63, v63
	v_add_f32_e32 v132, v128, v129
	v_add_f32_e32 v132, v130, v132
	v_add_f32_e32 v132, v131, v132
	ds_bpermute_b32 v138, v108, v132
	s_waitcnt lgkmcnt(0)
	v_add_f32_e32 v132, v132, v138
	ds_bpermute_b32 v138, v109, v132
	s_waitcnt lgkmcnt(0)
	v_add_f32_e32 v132, v132, v138
	ds_bpermute_b32 v138, v110, v132
	s_waitcnt lgkmcnt(0)
	v_add_f32_e32 v132, v132, v138
	ds_bpermute_b32 v138, v111, v132
	s_waitcnt lgkmcnt(0)
	v_add_f32_e32 v132, v132, v138
	ds_bpermute_b32 v138, v112, v132
	s_waitcnt lgkmcnt(0)
	v_add_f32_e32 v132, v132, v138
	ds_bpermute_b32 v138, v113, v132
	s_waitcnt lgkmcnt(0)
	v_add_f32_e32 v132, v132, v138
	v_fmamk_f32 v132, v132, 0x3a800000, v177
	v_mov_b32_e32 v135, 0x800000
	v_cmp_gt_f32_e32 vcc, v135, v132
	v_mul_f32_e32 v133, 0x4b800000, v132
	s_nop 1
	v_cndmask_b32_e32 v132, v132, v133, vcc
	v_rsq_f32_e32 v132, v132
	s_nop 0
	v_mul_f32_e32 v133, 0x45800000, v132
	v_cndmask_b32_e32 v134, v132, v133, vcc
	v_mul_f32_e32 v48, v48, v88
	v_mul_f32_e32 v49, v49, v89
	v_mul_f32_e32 v50, v50, v90
	v_mul_f32_e32 v51, v51, v91
	v_mul_f32_e32 v52, v52, v92
	v_mul_f32_e32 v53, v53, v93
	v_mul_f32_e32 v54, v54, v94
	v_mul_f32_e32 v55, v55, v95
	v_mul_f32_e32 v56, v56, v96
	v_mul_f32_e32 v57, v57, v97
	v_mul_f32_e32 v58, v58, v98
	v_mul_f32_e32 v59, v59, v99
	v_mul_f32_e32 v60, v60, v100
	v_mul_f32_e32 v61, v61, v101
	v_mul_f32_e32 v62, v62, v102
	v_mul_f32_e32 v63, v63, v103
	v_mul_f32_e32 v48, v48, v134
	v_mul_f32_e32 v49, v49, v134
	v_mul_f32_e32 v50, v50, v134
	v_mul_f32_e32 v51, v51, v134
	v_mul_f32_e32 v52, v52, v134
	v_mul_f32_e32 v53, v53, v134
	v_mul_f32_e32 v54, v54, v134
	v_mul_f32_e32 v55, v55, v134
	v_mul_f32_e32 v56, v56, v134
	v_mul_f32_e32 v57, v57, v134
	v_mul_f32_e32 v58, v58, v134
	v_mul_f32_e32 v59, v59, v134
	v_mul_f32_e32 v60, v60, v134
	v_mul_f32_e32 v61, v61, v134
	v_mul_f32_e32 v62, v62, v134
	v_mul_f32_e32 v63, v63, v134
	v_cvt_pk_bf16_f32 v120, v48, v49
	v_cvt_pk_bf16_f32 v121, v50, v51
	v_cvt_pk_bf16_f32 v122, v52, v53
	v_cvt_pk_bf16_f32 v123, v54, v55
	v_cvt_pk_bf16_f32 v124, v56, v57
	v_cvt_pk_bf16_f32 v125, v58, v59
	v_cvt_pk_bf16_f32 v126, v60, v61
	v_cvt_pk_bf16_f32 v127, v62, v63
	global_store_dwordx2 v119, v[120:121], s[4:5] nt
	global_store_dwordx2 v119, v[122:123], s[4:5] offset:512 nt
	global_store_dwordx2 v119, v[124:125], s[4:5] offset:1024 nt
	global_store_dwordx2 v119, v[126:127], s[4:5] offset:1536 nt
.LnrmA_skip2:
	s_addk_i32 s36, 0x1800
	s_cmpk_lt_i32 s36, 0x4100
	s_cbranch_scc1 .LnrmA_loop

.LBB0_1537:
	s_or_b64 exec, exec, s[12:13]
	s_mov_b64 s[0:1], -1
	s_and_b64 vcc, exec, s[42:43]
	s_waitcnt lgkmcnt(0)
	s_barrier
	s_cbranch_vccz .LBB0_1555
	v_mov_b32_e32 v0, v136
	s_nop 0
	v_lshrrev_b32_e32 v104, 6, v136
	v_and_b32_e32 v105, 63, v136
	v_readfirstlane_b32 s36, v104
	v_lshlrev_b32_e32 v106, 4, v105
	v_lshlrev_b32_e32 v107, 3, v105
	s_add_i32 s36, s82, s36
	s_cmpk_lt_i32 s36, 0x4100
	s_cbranch_scc0 .LnrmB_done
	v_xor_b32_e32 v108, 32, v105
	v_xor_b32_e32 v109, 16, v105
	v_xor_b32_e32 v110, 8, v105
	v_xor_b32_e32 v111, 4, v105
	v_xor_b32_e32 v112, 2, v105
	v_xor_b32_e32 v113, 1, v105
	v_lshlrev_b32_e32 v108, 2, v108
	v_lshlrev_b32_e32 v109, 2, v109
	v_lshlrev_b32_e32 v110, 2, v110
	v_lshlrev_b32_e32 v111, 2, v111
	v_lshlrev_b32_e32 v112, 2, v112
	v_lshlrev_b32_e32 v113, 2, v113
	v_readlane_b32 s42, v249, 60
	v_readlane_b32 s0, v248, 2
	v_readlane_b32 s1, v248, 3
	v_readlane_b32 s12, v248, 0
	v_readlane_b32 s13, v248, 1
	v_readlane_b32 s40, v252, 44
	v_readlane_b32 s41, v252, 45
	s_nop 4
	global_load_dwordx4 v[72:75], v106, s[0:1]
	global_load_dwordx4 v[76:79], v106, s[0:1] offset:1024
	global_load_dwordx4 v[80:83], v106, s[0:1] offset:2048
	global_load_dwordx4 v[84:87], v106, s[0:1] offset:3072
	s_cmp_eq_u32 s42, 0
	s_cbranch_scc1 .LnrmB_loop
	global_load_dwordx4 v[88:91], v106, s[12:13]
	global_load_dwordx4 v[92:95], v106, s[12:13] offset:1024
	global_load_dwordx4 v[96:99], v106, s[12:13] offset:2048
	global_load_dwordx4 v[100:103], v106, s[12:13] offset:3072
.LnrmB_loop:
	s_mov_b32 s37, s36
	s_cmpk_gt_i32 s37, 0x207f
	s_cselect_b32 s43, 0x2080, 0
	s_cselect_b32 vcc_lo, 0x2000, 0
	s_cselect_b32 vcc_hi, 0x80, 0
	s_sub_i32 s43, s37, s43
	s_add_i32 vcc_lo, vcc_lo, s43
	s_addk_i32 vcc_lo, 0xff80
	s_add_i32 vcc_hi, vcc_hi, s43
	s_cmpk_lt_i32 s43, 0x80
	s_cselect_b32 vcc_lo, vcc_hi, vcc_lo
	s_cselect_b32 s0, s40, s92
	s_cselect_b32 s1, s41, s93
	s_lshl_b32 vcc_lo, vcc_lo, 12
	s_lshl_b32 vcc_hi, s37, 11
	v_add_u32_e32 v114, vcc_lo, v106
	v_add_u32_e32 v117, vcc_hi, v107
	global_load_dwordx2 v[16:17], v117, s[4:5] nt
	global_load_dwordx2 v[18:19], v117, s[4:5] offset:512 nt
	global_load_dwordx2 v[20:21], v117, s[4:5] offset:1024 nt
	global_load_dwordx2 v[22:23], v117, s[4:5] offset:1536 nt
	global_load_dwordx4 v[0:3], v114, s[0:1] nt
	global_load_dwordx4 v[4:7], v114, s[0:1] offset:1024 nt
	global_load_dwordx4 v[8:11], v114, s[0:1] offset:2048 nt
	global_load_dwordx4 v[12:15], v114, s[0:1] offset:3072 nt
	s_add_i32 s37, s36, 2048
	s_cmpk_lt_i32 s37, 0x4100
	s_cselect_b32 s37, s37, s36
	s_cmpk_gt_i32 s37, 0x207f
	s_cselect_b32 s43, 0x2080, 0
	s_cselect_b32 vcc_lo, 0x2000, 0
	s_cselect_b32 vcc_hi, 0x80, 0
	s_sub_i32 s43, s37, s43
	s_add_i32 vcc_lo, vcc_lo, s43
	s_addk_i32 vcc_lo, 0xff80
	s_add_i32 vcc_hi, vcc_hi, s43
	s_cmpk_lt_i32 s43, 0x80
	s_cselect_b32 vcc_lo, vcc_hi, vcc_lo
	s_cselect_b32 s12, s40, s92
	s_cselect_b32 s13, s41, s93
	s_lshl_b32 vcc_lo, vcc_lo, 12
	s_lshl_b32 vcc_hi, s37, 11
	v_add_u32_e32 v115, vcc_lo, v106
	v_add_u32_e32 v118, vcc_hi, v107
	global_load_dwordx2 v[40:41], v118, s[4:5] nt
	global_load_dwordx2 v[42:43], v118, s[4:5] offset:512 nt
	global_load_dwordx2 v[44:45], v118, s[4:5] offset:1024 nt
	global_load_dwordx2 v[46:47], v118, s[4:5] offset:1536 nt
	global_load_dwordx4 v[24:27], v115, s[12:13] nt
	global_load_dwordx4 v[28:31], v115, s[12:13] offset:1024 nt
	global_load_dwordx4 v[32:35], v115, s[12:13] offset:2048 nt
	global_load_dwordx4 v[36:39], v115, s[12:13] offset:3072 nt
	s_add_i32 s37, s36, 4096
	s_cmpk_lt_i32 s37, 0x4100
	s_cselect_b32 s37, s37, s36
	s_cmpk_gt_i32 s37, 0x207f
	s_cselect_b32 s43, 0x2080, 0
	s_cselect_b32 vcc_lo, 0x2000, 0
	s_cselect_b32 vcc_hi, 0x80, 0
	s_sub_i32 s43, s37, s43
	s_add_i32 vcc_lo, vcc_lo, s43
	s_addk_i32 vcc_lo, 0xff80
	s_add_i32 vcc_hi, vcc_hi, s43
	s_cmpk_lt_i32 s43, 0x80
	s_cselect_b32 vcc_lo, vcc_hi, vcc_lo
	s_cselect_b32 s38, s40, s92
	s_cselect_b32 s39, s41, s93
	s_lshl_b32 vcc_lo, vcc_lo, 12
	s_lshl_b32 vcc_hi, s37, 11
	v_add_u32_e32 v116, vcc_lo, v106
	v_add_u32_e32 v119, vcc_hi, v107
	global_load_dwordx2 v[64:65], v119, s[4:5] nt
	global_load_dwordx2 v[66:67], v119, s[4:5] offset:512 nt
	global_load_dwordx2 v[68:69], v119, s[4:5] offset:1024 nt
	global_load_dwordx2 v[70:71], v119, s[4:5] offset:1536 nt
	global_load_dwordx4 v[48:51], v116, s[38:39] nt
	global_load_dwordx4 v[52:55], v116, s[38:39] offset:1024 nt
	global_load_dwordx4 v[56:59], v116, s[38:39] offset:2048 nt
	global_load_dwordx4 v[60:63], v116, s[38:39] offset:3072 nt
	s_waitcnt vmcnt(16)
	v_lshlrev_b32_e32 v120, 16, v16
	v_and_b32_e32 v16, 0xffff0000, v16
	v_lshlrev_b32_e32 v121, 16, v17
	v_and_b32_e32 v17, 0xffff0000, v17
	v_lshlrev_b32_e32 v122, 16, v18
	v_and_b32_e32 v18, 0xffff0000, v18
	v_lshlrev_b32_e32 v123, 16, v19
	v_and_b32_e32 v19, 0xffff0000, v19
	v_lshlrev_b32_e32 v124, 16, v20
	v_and_b32_e32 v20, 0xffff0000, v20
	v_lshlrev_b32_e32 v125, 16, v21
	v_and_b32_e32 v21, 0xffff0000, v21
	v_lshlrev_b32_e32 v126, 16, v22
	v_and_b32_e32 v22, 0xffff0000, v22
	v_lshlrev_b32_e32 v127, 16, v23
	v_and_b32_e32 v23, 0xffff0000, v23
	v_mul_f32_e32 v128, v16, v16
	v_mul_f32_e32 v129, v18, v18
	v_mul_f32_e32 v130, v20, v20
	v_mul_f32_e32 v131, v22, v22
	v_fmac_f32_e32 v128, v120, v120
	v_fmac_f32_e32 v129, v122, v122
	v_fmac_f32_e32 v130, v124, v124
	v_fmac_f32_e32 v131, v126, v126
	v_fmac_f32_e32 v128, v121, v121
	v_fmac_f32_e32 v129, v123, v123
	v_fmac_f32_e32 v130, v125, v125
	v_fmac_f32_e32 v131, v127, v127
	v_fmac_f32_e32 v128, v17, v17
	v_fmac_f32_e32 v129, v19, v19
	v_fmac_f32_e32 v130, v21, v21
	v_fmac_f32_e32 v131, v23, v23
	v_add_f32_e32 v132, v128, v129
	v_add_f32_e32 v132, v132, v130
	v_add_f32_e32 v132, v132, v131
	ds_bpermute_b32 v138, v108, v132
	s_waitcnt lgkmcnt(0)
	v_add_f32_e32 v132, v132, v138
	ds_bpermute_b32 v138, v109, v132
	s_waitcnt lgkmcnt(0)
	v_add_f32_e32 v132, v132, v138
	ds_bpermute_b32 v138, v110, v132
	s_waitcnt lgkmcnt(0)
	v_add_f32_e32 v132, v132, v138
	ds_bpermute_b32 v138, v111, v132
	s_waitcnt lgkmcnt(0)
	v_add_f32_e32 v132, v132, v138
	ds_bpermute_b32 v138, v112, v132
	s_waitcnt lgkmcnt(0)
	v_add_f32_e32 v132, v132, v138
	ds_bpermute_b32 v138, v113, v132
	s_waitcnt lgkmcnt(0)
	v_add_f32_e32 v132, v132, v138
	v_fmamk_f32 v132, v132, 0x3a800000, v177
	v_mov_b32_e32 v135, 0x800000
	v_cmp_gt_f32_e32 vcc, v135, v132
	v_mul_f32_e32 v133, 0x4b800000, v132
	s_nop 1
	v_cndmask_b32_e32 v132, v132, v133, vcc
	v_rsq_f32_e32 v132, v132
	s_nop 0
	v_mul_f32_e32 v133, 0x45800000, v132
	v_cndmask_b32_e32 v132, v132, v133, vcc
	v_mul_f32_e32 v134, 0.5, v132
	v_mul_f32_e32 v120, v72, v120
	v_mul_f32_e32 v16, v73, v16
	v_mul_f32_e32 v121, v74, v121
	v_mul_f32_e32 v17, v75, v17
	v_mul_f32_e32 v122, v76, v122
	v_mul_f32_e32 v18, v77, v18
	v_mul_f32_e32 v123, v78, v123
	v_mul_f32_e32 v19, v79, v19
	v_mul_f32_e32 v124, v80, v124
	v_mul_f32_e32 v20, v81, v20
	v_mul_f32_e32 v125, v82, v125
	v_mul_f32_e32 v21, v83, v21
	v_mul_f32_e32 v126, v84, v126
	v_mul_f32_e32 v22, v85, v22
	v_mul_f32_e32 v127, v86, v127
	v_mul_f32_e32 v23, v87, v23
	v_fmac_f32_e32 v0, v120, v134
	v_fmac_f32_e32 v1, v16, v134
	v_fmac_f32_e32 v2, v121, v134
	v_fmac_f32_e32 v3, v17, v134
	v_fmac_f32_e32 v4, v122, v134
	v_fmac_f32_e32 v5, v18, v134
	v_fmac_f32_e32 v6, v123, v134
	v_fmac_f32_e32 v7, v19, v134
	v_fmac_f32_e32 v8, v124, v134
	v_fmac_f32_e32 v9, v20, v134
	v_fmac_f32_e32 v10, v125, v134
	v_fmac_f32_e32 v11, v21, v134
	v_fmac_f32_e32 v12, v126, v134
	v_fmac_f32_e32 v13, v22, v134
	v_fmac_f32_e32 v14, v127, v134
	v_fmac_f32_e32 v15, v23, v134
	global_store_dwordx4 v114, v[0:3], s[0:1] nt
	global_store_dwordx4 v114, v[4:7], s[0:1] offset:1024 nt
	global_store_dwordx4 v114, v[8:11], s[0:1] offset:2048 nt
	global_store_dwordx4 v114, v[12:15], s[0:1] offset:3072 nt
	s_cmp_eq_u32 s42, 0
	s_cbranch_scc1 .LnrmB_nopre0
	v_mul_f32_e32 v128, v1, v1
	v_mul_f32_e32 v129, v5, v5
	v_mul_f32_e32 v130, v9, v9
	v_mul_f32_e32 v131, v13, v13
	v_fmac_f32_e32 v128, v0, v0
	v_fmac_f32_e32 v129, v4, v4
	v_fmac_f32_e32 v130, v8, v8
	v_fmac_f32_e32 v131, v12, v12
	v_fmac_f32_e32 v128, v2, v2
	v_fmac_f32_e32 v129, v6, v6
	v_fmac_f32_e32 v130, v10, v10
	v_fmac_f32_e32 v131, v14, v14
	v_fmac_f32_e32 v128, v3, v3
	v_fmac_f32_e32 v129, v7, v7
	v_fmac_f32_e32 v130, v11, v11
	v_fmac_f32_e32 v131, v15, v15
	v_add_f32_e32 v132, v128, v129
	v_add_f32_e32 v132, v130, v132
	v_add_f32_e32 v132, v131, v132
	ds_bpermute_b32 v138, v108, v132
	s_waitcnt lgkmcnt(0)
	v_add_f32_e32 v132, v132, v138
	ds_bpermute_b32 v138, v109, v132
	s_waitcnt lgkmcnt(0)
	v_add_f32_e32 v132, v132, v138
	ds_bpermute_b32 v138, v110, v132
	s_waitcnt lgkmcnt(0)
	v_add_f32_e32 v132, v132, v138
	ds_bpermute_b32 v138, v111, v132
	s_waitcnt lgkmcnt(0)
	v_add_f32_e32 v132, v132, v138
	ds_bpermute_b32 v138, v112, v132
	s_waitcnt lgkmcnt(0)
	v_add_f32_e32 v132, v132, v138
	ds_bpermute_b32 v138, v113, v132
	s_waitcnt lgkmcnt(0)
	v_add_f32_e32 v132, v132, v138
	v_fmamk_f32 v132, v132, 0x3a800000, v177
	v_mov_b32_e32 v135, 0x800000
	v_cmp_gt_f32_e32 vcc, v135, v132
	v_mul_f32_e32 v133, 0x4b800000, v132
	s_nop 1
	v_cndmask_b32_e32 v132, v132, v133, vcc
	v_rsq_f32_e32 v132, v132
	s_nop 0
	v_mul_f32_e32 v133, 0x45800000, v132
	v_cndmask_b32_e32 v134, v132, v133, vcc
	v_mul_f32_e32 v0, v0, v88
	v_mul_f32_e32 v1, v1, v89
	v_mul_f32_e32 v2, v2, v90
	v_mul_f32_e32 v3, v3, v91
	v_mul_f32_e32 v4, v4, v92
	v_mul_f32_e32 v5, v5, v93
	v_mul_f32_e32 v6, v6, v94
	v_mul_f32_e32 v7, v7, v95
	v_mul_f32_e32 v8, v8, v96
	v_mul_f32_e32 v9, v9, v97
	v_mul_f32_e32 v10, v10, v98
	v_mul_f32_e32 v11, v11, v99
	v_mul_f32_e32 v12, v12, v100
	v_mul_f32_e32 v13, v13, v101
	v_mul_f32_e32 v14, v14, v102
	v_mul_f32_e32 v15, v15, v103
	v_mul_f32_e32 v0, v0, v134
	v_mul_f32_e32 v1, v1, v134
	v_mul_f32_e32 v2, v2, v134
	v_mul_f32_e32 v3, v3, v134
	v_mul_f32_e32 v4, v4, v134
	v_mul_f32_e32 v5, v5, v134
	v_mul_f32_e32 v6, v6, v134
	v_mul_f32_e32 v7, v7, v134
	v_mul_f32_e32 v8, v8, v134
	v_mul_f32_e32 v9, v9, v134
	v_mul_f32_e32 v10, v10, v134
	v_mul_f32_e32 v11, v11, v134
	v_mul_f32_e32 v12, v12, v134
	v_mul_f32_e32 v13, v13, v134
	v_mul_f32_e32 v14, v14, v134
	v_mul_f32_e32 v15, v15, v134
	v_cvt_pk_bf16_f32 v120, v0, v1
	v_cvt_pk_bf16_f32 v121, v2, v3
	v_cvt_pk_bf16_f32 v122, v4, v5
	v_cvt_pk_bf16_f32 v123, v6, v7
	v_cvt_pk_bf16_f32 v124, v8, v9
	v_cvt_pk_bf16_f32 v125, v10, v11
	v_cvt_pk_bf16_f32 v126, v12, v13
	v_cvt_pk_bf16_f32 v127, v14, v15
	global_store_dwordx2 v117, v[120:121], s[4:5] nt
	global_store_dwordx2 v117, v[122:123], s[4:5] offset:512 nt
	global_store_dwordx2 v117, v[124:125], s[4:5] offset:1024 nt
	global_store_dwordx2 v117, v[126:127], s[4:5] offset:1536 nt
.LnrmB_nopre0:
	s_add_i32 s37, s36, 2048
	s_cmpk_lt_i32 s37, 0x4100
	s_cbranch_scc0 .LnrmB_skip1
	s_waitcnt vmcnt(12)
	v_lshlrev_b32_e32 v120, 16, v40
	v_and_b32_e32 v40, 0xffff0000, v40
	v_lshlrev_b32_e32 v121, 16, v41
	v_and_b32_e32 v41, 0xffff0000, v41
	v_lshlrev_b32_e32 v122, 16, v42
	v_and_b32_e32 v42, 0xffff0000, v42
	v_lshlrev_b32_e32 v123, 16, v43
	v_and_b32_e32 v43, 0xffff0000, v43
	v_lshlrev_b32_e32 v124, 16, v44
	v_and_b32_e32 v44, 0xffff0000, v44
	v_lshlrev_b32_e32 v125, 16, v45
	v_and_b32_e32 v45, 0xffff0000, v45
	v_lshlrev_b32_e32 v126, 16, v46
	v_and_b32_e32 v46, 0xffff0000, v46
	v_lshlrev_b32_e32 v127, 16, v47
	v_and_b32_e32 v47, 0xffff0000, v47
	v_mul_f32_e32 v128, v40, v40
	v_mul_f32_e32 v129, v42, v42
	v_mul_f32_e32 v130, v44, v44
	v_mul_f32_e32 v131, v46, v46
	v_fmac_f32_e32 v128, v120, v120
	v_fmac_f32_e32 v129, v122, v122
	v_fmac_f32_e32 v130, v124, v124
	v_fmac_f32_e32 v131, v126, v126
	v_fmac_f32_e32 v128, v121, v121
	v_fmac_f32_e32 v129, v123, v123
	v_fmac_f32_e32 v130, v125, v125
	v_fmac_f32_e32 v131, v127, v127
	v_fmac_f32_e32 v128, v41, v41
	v_fmac_f32_e32 v129, v43, v43
	v_fmac_f32_e32 v130, v45, v45
	v_fmac_f32_e32 v131, v47, v47
	v_add_f32_e32 v132, v128, v129
	v_add_f32_e32 v132, v132, v130
	v_add_f32_e32 v132, v132, v131
	ds_bpermute_b32 v138, v108, v132
	s_waitcnt lgkmcnt(0)
	v_add_f32_e32 v132, v132, v138
	ds_bpermute_b32 v138, v109, v132
	s_waitcnt lgkmcnt(0)
	v_add_f32_e32 v132, v132, v138
	ds_bpermute_b32 v138, v110, v132
	s_waitcnt lgkmcnt(0)
	v_add_f32_e32 v132, v132, v138
	ds_bpermute_b32 v138, v111, v132
	s_waitcnt lgkmcnt(0)
	v_add_f32_e32 v132, v132, v138
	ds_bpermute_b32 v138, v112, v132
	s_waitcnt lgkmcnt(0)
	v_add_f32_e32 v132, v132, v138
	ds_bpermute_b32 v138, v113, v132
	s_waitcnt lgkmcnt(0)
	v_add_f32_e32 v132, v132, v138
	v_fmamk_f32 v132, v132, 0x3a800000, v177
	v_mov_b32_e32 v135, 0x800000
	v_cmp_gt_f32_e32 vcc, v135, v132
	v_mul_f32_e32 v133, 0x4b800000, v132
	s_nop 1
	v_cndmask_b32_e32 v132, v132, v133, vcc
	v_rsq_f32_e32 v132, v132
	s_nop 0
	v_mul_f32_e32 v133, 0x45800000, v132
	v_cndmask_b32_e32 v132, v132, v133, vcc
	v_mul_f32_e32 v134, 0.5, v132
	v_mul_f32_e32 v120, v72, v120
	v_mul_f32_e32 v40, v73, v40
	v_mul_f32_e32 v121, v74, v121
	v_mul_f32_e32 v41, v75, v41
	v_mul_f32_e32 v122, v76, v122
	v_mul_f32_e32 v42, v77, v42
	v_mul_f32_e32 v123, v78, v123
	v_mul_f32_e32 v43, v79, v43
	v_mul_f32_e32 v124, v80, v124
	v_mul_f32_e32 v44, v81, v44
	v_mul_f32_e32 v125, v82, v125
	v_mul_f32_e32 v45, v83, v45
	v_mul_f32_e32 v126, v84, v126
	v_mul_f32_e32 v46, v85, v46
	v_mul_f32_e32 v127, v86, v127
	v_mul_f32_e32 v47, v87, v47
	v_fmac_f32_e32 v24, v120, v134
	v_fmac_f32_e32 v25, v40, v134
	v_fmac_f32_e32 v26, v121, v134
	v_fmac_f32_e32 v27, v41, v134
	v_fmac_f32_e32 v28, v122, v134
	v_fmac_f32_e32 v29, v42, v134
	v_fmac_f32_e32 v30, v123, v134
	v_fmac_f32_e32 v31, v43, v134
	v_fmac_f32_e32 v32, v124, v134
	v_fmac_f32_e32 v33, v44, v134
	v_fmac_f32_e32 v34, v125, v134
	v_fmac_f32_e32 v35, v45, v134
	v_fmac_f32_e32 v36, v126, v134
	v_fmac_f32_e32 v37, v46, v134
	v_fmac_f32_e32 v38, v127, v134
	v_fmac_f32_e32 v39, v47, v134
	global_store_dwordx4 v115, v[24:27], s[12:13] nt
	global_store_dwordx4 v115, v[28:31], s[12:13] offset:1024 nt
	global_store_dwordx4 v115, v[32:35], s[12:13] offset:2048 nt
	global_store_dwordx4 v115, v[36:39], s[12:13] offset:3072 nt
	s_cmp_eq_u32 s42, 0
	s_cbranch_scc1 .LnrmB_skip1
	v_mul_f32_e32 v128, v25, v25
	v_mul_f32_e32 v129, v29, v29
	v_mul_f32_e32 v130, v33, v33
	v_mul_f32_e32 v131, v37, v37
	v_fmac_f32_e32 v128, v24, v24
	v_fmac_f32_e32 v129, v28, v28
	v_fmac_f32_e32 v130, v32, v32
	v_fmac_f32_e32 v131, v36, v36
	v_fmac_f32_e32 v128, v26, v26
	v_fmac_f32_e32 v129, v30, v30
	v_fmac_f32_e32 v130, v34, v34
	v_fmac_f32_e32 v131, v38, v38
	v_fmac_f32_e32 v128, v27, v27
	v_fmac_f32_e32 v129, v31, v31
	v_fmac_f32_e32 v130, v35, v35
	v_fmac_f32_e32 v131, v39, v39
	v_add_f32_e32 v132, v128, v129
	v_add_f32_e32 v132, v130, v132
	v_add_f32_e32 v132, v131, v132
	ds_bpermute_b32 v138, v108, v132
	s_waitcnt lgkmcnt(0)
	v_add_f32_e32 v132, v132, v138
	ds_bpermute_b32 v138, v109, v132
	s_waitcnt lgkmcnt(0)
	v_add_f32_e32 v132, v132, v138
	ds_bpermute_b32 v138, v110, v132
	s_waitcnt lgkmcnt(0)
	v_add_f32_e32 v132, v132, v138
	ds_bpermute_b32 v138, v111, v132
	s_waitcnt lgkmcnt(0)
	v_add_f32_e32 v132, v132, v138
	ds_bpermute_b32 v138, v112, v132
	s_waitcnt lgkmcnt(0)
	v_add_f32_e32 v132, v132, v138
	ds_bpermute_b32 v138, v113, v132
	s_waitcnt lgkmcnt(0)
	v_add_f32_e32 v132, v132, v138
	v_fmamk_f32 v132, v132, 0x3a800000, v177
	v_mov_b32_e32 v135, 0x800000
	v_cmp_gt_f32_e32 vcc, v135, v132
	v_mul_f32_e32 v133, 0x4b800000, v132
	s_nop 1
	v_cndmask_b32_e32 v132, v132, v133, vcc
	v_rsq_f32_e32 v132, v132
	s_nop 0
	v_mul_f32_e32 v133, 0x45800000, v132
	v_cndmask_b32_e32 v134, v132, v133, vcc
	v_mul_f32_e32 v24, v24, v88
	v_mul_f32_e32 v25, v25, v89
	v_mul_f32_e32 v26, v26, v90
	v_mul_f32_e32 v27, v27, v91
	v_mul_f32_e32 v28, v28, v92
	v_mul_f32_e32 v29, v29, v93
	v_mul_f32_e32 v30, v30, v94
	v_mul_f32_e32 v31, v31, v95
	v_mul_f32_e32 v32, v32, v96
	v_mul_f32_e32 v33, v33, v97
	v_mul_f32_e32 v34, v34, v98
	v_mul_f32_e32 v35, v35, v99
	v_mul_f32_e32 v36, v36, v100
	v_mul_f32_e32 v37, v37, v101
	v_mul_f32_e32 v38, v38, v102
	v_mul_f32_e32 v39, v39, v103
	v_mul_f32_e32 v24, v24, v134
	v_mul_f32_e32 v25, v25, v134
	v_mul_f32_e32 v26, v26, v134
	v_mul_f32_e32 v27, v27, v134
	v_mul_f32_e32 v28, v28, v134
	v_mul_f32_e32 v29, v29, v134
	v_mul_f32_e32 v30, v30, v134
	v_mul_f32_e32 v31, v31, v134
	v_mul_f32_e32 v32, v32, v134
	v_mul_f32_e32 v33, v33, v134
	v_mul_f32_e32 v34, v34, v134
	v_mul_f32_e32 v35, v35, v134
	v_mul_f32_e32 v36, v36, v134
	v_mul_f32_e32 v37, v37, v134
	v_mul_f32_e32 v38, v38, v134
	v_mul_f32_e32 v39, v39, v134
	v_cvt_pk_bf16_f32 v120, v24, v25
	v_cvt_pk_bf16_f32 v121, v26, v27
	v_cvt_pk_bf16_f32 v122, v28, v29
	v_cvt_pk_bf16_f32 v123, v30, v31
	v_cvt_pk_bf16_f32 v124, v32, v33
	v_cvt_pk_bf16_f32 v125, v34, v35
	v_cvt_pk_bf16_f32 v126, v36, v37
	v_cvt_pk_bf16_f32 v127, v38, v39
	global_store_dwordx2 v118, v[120:121], s[4:5] nt
	global_store_dwordx2 v118, v[122:123], s[4:5] offset:512 nt
	global_store_dwordx2 v118, v[124:125], s[4:5] offset:1024 nt
	global_store_dwordx2 v118, v[126:127], s[4:5] offset:1536 nt
.LnrmB_skip1:
	s_add_i32 s37, s36, 4096
	s_cmpk_lt_i32 s37, 0x4100
	s_cbranch_scc0 .LnrmB_skip2
	s_waitcnt vmcnt(8)
	v_lshlrev_b32_e32 v120, 16, v64
	v_and_b32_e32 v64, 0xffff0000, v64
	v_lshlrev_b32_e32 v121, 16, v65
	v_and_b32_e32 v65, 0xffff0000, v65
	v_lshlrev_b32_e32 v122, 16, v66
	v_and_b32_e32 v66, 0xffff0000, v66
	v_lshlrev_b32_e32 v123, 16, v67
	v_and_b32_e32 v67, 0xffff0000, v67
	v_lshlrev_b32_e32 v124, 16, v68
	v_and_b32_e32 v68, 0xffff0000, v68
	v_lshlrev_b32_e32 v125, 16, v69
	v_and_b32_e32 v69, 0xffff0000, v69
	v_lshlrev_b32_e32 v126, 16, v70
	v_and_b32_e32 v70, 0xffff0000, v70
	v_lshlrev_b32_e32 v127, 16, v71
	v_and_b32_e32 v71, 0xffff0000, v71
	v_mul_f32_e32 v128, v64, v64
	v_mul_f32_e32 v129, v66, v66
	v_mul_f32_e32 v130, v68, v68
	v_mul_f32_e32 v131, v70, v70
	v_fmac_f32_e32 v128, v120, v120
	v_fmac_f32_e32 v129, v122, v122
	v_fmac_f32_e32 v130, v124, v124
	v_fmac_f32_e32 v131, v126, v126
	v_fmac_f32_e32 v128, v121, v121
	v_fmac_f32_e32 v129, v123, v123
	v_fmac_f32_e32 v130, v125, v125
	v_fmac_f32_e32 v131, v127, v127
	v_fmac_f32_e32 v128, v65, v65
	v_fmac_f32_e32 v129, v67, v67
	v_fmac_f32_e32 v130, v69, v69
	v_fmac_f32_e32 v131, v71, v71
	v_add_f32_e32 v132, v128, v129
	v_add_f32_e32 v132, v132, v130
	v_add_f32_e32 v132, v132, v131
	ds_bpermute_b32 v138, v108, v132
	s_waitcnt lgkmcnt(0)
	v_add_f32_e32 v132, v132, v138
	ds_bpermute_b32 v138, v109, v132
	s_waitcnt lgkmcnt(0)
	v_add_f32_e32 v132, v132, v138
	ds_bpermute_b32 v138, v110, v132
	s_waitcnt lgkmcnt(0)
	v_add_f32_e32 v132, v132, v138
	ds_bpermute_b32 v138, v111, v132
	s_waitcnt lgkmcnt(0)
	v_add_f32_e32 v132, v132, v138
	ds_bpermute_b32 v138, v112, v132
	s_waitcnt lgkmcnt(0)
	v_add_f32_e32 v132, v132, v138
	ds_bpermute_b32 v138, v113, v132
	s_waitcnt lgkmcnt(0)
	v_add_f32_e32 v132, v132, v138
	v_fmamk_f32 v132, v132, 0x3a800000, v177
	v_mov_b32_e32 v135, 0x800000
	v_cmp_gt_f32_e32 vcc, v135, v132
	v_mul_f32_e32 v133, 0x4b800000, v132
	s_nop 1
	v_cndmask_b32_e32 v132, v132, v133, vcc
	v_rsq_f32_e32 v132, v132
	s_nop 0
	v_mul_f32_e32 v133, 0x45800000, v132
	v_cndmask_b32_e32 v132, v132, v133, vcc
	v_mul_f32_e32 v134, 0.5, v132
	v_mul_f32_e32 v120, v72, v120
	v_mul_f32_e32 v64, v73, v64
	v_mul_f32_e32 v121, v74, v121
	v_mul_f32_e32 v65, v75, v65
	v_mul_f32_e32 v122, v76, v122
	v_mul_f32_e32 v66, v77, v66
	v_mul_f32_e32 v123, v78, v123
	v_mul_f32_e32 v67, v79, v67
	v_mul_f32_e32 v124, v80, v124
	v_mul_f32_e32 v68, v81, v68
	v_mul_f32_e32 v125, v82, v125
	v_mul_f32_e32 v69, v83, v69
	v_mul_f32_e32 v126, v84, v126
	v_mul_f32_e32 v70, v85, v70
	v_mul_f32_e32 v127, v86, v127
	v_mul_f32_e32 v71, v87, v71
	v_fmac_f32_e32 v48, v120, v134
	v_fmac_f32_e32 v49, v64, v134
	v_fmac_f32_e32 v50, v121, v134
	v_fmac_f32_e32 v51, v65, v134
	v_fmac_f32_e32 v52, v122, v134
	v_fmac_f32_e32 v53, v66, v134
	v_fmac_f32_e32 v54, v123, v134
	v_fmac_f32_e32 v55, v67, v134
	v_fmac_f32_e32 v56, v124, v134
	v_fmac_f32_e32 v57, v68, v134
	v_fmac_f32_e32 v58, v125, v134
	v_fmac_f32_e32 v59, v69, v134
	v_fmac_f32_e32 v60, v126, v134
	v_fmac_f32_e32 v61, v70, v134
	v_fmac_f32_e32 v62, v127, v134
	v_fmac_f32_e32 v63, v71, v134
	global_store_dwordx4 v116, v[48:51], s[38:39] nt
	global_store_dwordx4 v116, v[52:55], s[38:39] offset:1024 nt
	global_store_dwordx4 v116, v[56:59], s[38:39] offset:2048 nt
	global_store_dwordx4 v116, v[60:63], s[38:39] offset:3072 nt
	s_cmp_eq_u32 s42, 0
	s_cbranch_scc1 .LnrmB_skip2
	v_mul_f32_e32 v128, v49, v49
	v_mul_f32_e32 v129, v53, v53
	v_mul_f32_e32 v130, v57, v57
	v_mul_f32_e32 v131, v61, v61
	v_fmac_f32_e32 v128, v48, v48
	v_fmac_f32_e32 v129, v52, v52
	v_fmac_f32_e32 v130, v56, v56
	v_fmac_f32_e32 v131, v60, v60
	v_fmac_f32_e32 v128, v50, v50
	v_fmac_f32_e32 v129, v54, v54
	v_fmac_f32_e32 v130, v58, v58
	v_fmac_f32_e32 v131, v62, v62
	v_fmac_f32_e32 v128, v51, v51
	v_fmac_f32_e32 v129, v55, v55
	v_fmac_f32_e32 v130, v59, v59
	v_fmac_f32_e32 v131, v63, v63
	v_add_f32_e32 v132, v128, v129
	v_add_f32_e32 v132, v130, v132
	v_add_f32_e32 v132, v131, v132
	ds_bpermute_b32 v138, v108, v132
	s_waitcnt lgkmcnt(0)
	v_add_f32_e32 v132, v132, v138
	ds_bpermute_b32 v138, v109, v132
	s_waitcnt lgkmcnt(0)
	v_add_f32_e32 v132, v132, v138
	ds_bpermute_b32 v138, v110, v132
	s_waitcnt lgkmcnt(0)
	v_add_f32_e32 v132, v132, v138
	ds_bpermute_b32 v138, v111, v132
	s_waitcnt lgkmcnt(0)
	v_add_f32_e32 v132, v132, v138
	ds_bpermute_b32 v138, v112, v132
	s_waitcnt lgkmcnt(0)
	v_add_f32_e32 v132, v132, v138
	ds_bpermute_b32 v138, v113, v132
	s_waitcnt lgkmcnt(0)
	v_add_f32_e32 v132, v132, v138
	v_fmamk_f32 v132, v132, 0x3a800000, v177
	v_mov_b32_e32 v135, 0x800000
	v_cmp_gt_f32_e32 vcc, v135, v132
	v_mul_f32_e32 v133, 0x4b800000, v132
	s_nop 1
	v_cndmask_b32_e32 v132, v132, v133, vcc
	v_rsq_f32_e32 v132, v132
	s_nop 0
	v_mul_f32_e32 v133, 0x45800000, v132
	v_cndmask_b32_e32 v134, v132, v133, vcc
	v_mul_f32_e32 v48, v48, v88
	v_mul_f32_e32 v49, v49, v89
	v_mul_f32_e32 v50, v50, v90
	v_mul_f32_e32 v51, v51, v91
	v_mul_f32_e32 v52, v52, v92
	v_mul_f32_e32 v53, v53, v93
	v_mul_f32_e32 v54, v54, v94
	v_mul_f32_e32 v55, v55, v95
	v_mul_f32_e32 v56, v56, v96
	v_mul_f32_e32 v57, v57, v97
	v_mul_f32_e32 v58, v58, v98
	v_mul_f32_e32 v59, v59, v99
	v_mul_f32_e32 v60, v60, v100
	v_mul_f32_e32 v61, v61, v101
	v_mul_f32_e32 v62, v62, v102
	v_mul_f32_e32 v63, v63, v103
	v_mul_f32_e32 v48, v48, v134
	v_mul_f32_e32 v49, v49, v134
	v_mul_f32_e32 v50, v50, v134
	v_mul_f32_e32 v51, v51, v134
	v_mul_f32_e32 v52, v52, v134
	v_mul_f32_e32 v53, v53, v134
	v_mul_f32_e32 v54, v54, v134
	v_mul_f32_e32 v55, v55, v134
	v_mul_f32_e32 v56, v56, v134
	v_mul_f32_e32 v57, v57, v134
	v_mul_f32_e32 v58, v58, v134
	v_mul_f32_e32 v59, v59, v134
	v_mul_f32_e32 v60, v60, v134
	v_mul_f32_e32 v61, v61, v134
	v_mul_f32_e32 v62, v62, v134
	v_mul_f32_e32 v63, v63, v134
	v_cvt_pk_bf16_f32 v120, v48, v49
	v_cvt_pk_bf16_f32 v121, v50, v51
	v_cvt_pk_bf16_f32 v122, v52, v53
	v_cvt_pk_bf16_f32 v123, v54, v55
	v_cvt_pk_bf16_f32 v124, v56, v57
	v_cvt_pk_bf16_f32 v125, v58, v59
	v_cvt_pk_bf16_f32 v126, v60, v61
	v_cvt_pk_bf16_f32 v127, v62, v63
	global_store_dwordx2 v119, v[120:121], s[4:5] nt
	global_store_dwordx2 v119, v[122:123], s[4:5] offset:512 nt
	global_store_dwordx2 v119, v[124:125], s[4:5] offset:1024 nt
	global_store_dwordx2 v119, v[126:127], s[4:5] offset:1536 nt

.LBB0_1555:
	s_andn2_b64 vcc, exec, s[0:1]
	s_cbranch_vccnz .LBB0_1573
	v_mov_b32_e32 v0, v136
	s_nop 0
	v_lshrrev_b32_e32 v104, 6, v136
	v_and_b32_e32 v105, 63, v136
	v_readfirstlane_b32 s36, v104
	v_lshlrev_b32_e32 v106, 4, v105
	v_lshlrev_b32_e32 v107, 3, v105
	s_add_i32 s36, s82, s36
	s_cmpk_lt_i32 s36, 0x4100
	s_cbranch_scc0 .LnrmC_done
	v_xor_b32_e32 v108, 32, v105
	v_xor_b32_e32 v109, 16, v105
	v_xor_b32_e32 v110, 8, v105
	v_xor_b32_e32 v111, 4, v105
	v_xor_b32_e32 v112, 2, v105
	v_xor_b32_e32 v113, 1, v105
	v_lshlrev_b32_e32 v108, 2, v108
	v_lshlrev_b32_e32 v109, 2, v109
	v_lshlrev_b32_e32 v110, 2, v110
	v_lshlrev_b32_e32 v111, 2, v111
	v_lshlrev_b32_e32 v112, 2, v112
	v_lshlrev_b32_e32 v113, 2, v113
	v_readlane_b32 s42, v252, 50
	v_readlane_b32 s0, v248, 6
	v_readlane_b32 s1, v248, 7
	v_readlane_b32 s12, v248, 4
	v_readlane_b32 s13, v248, 5
	v_readlane_b32 s40, v252, 44
	v_readlane_b32 s41, v252, 45
	s_nop 4
	global_load_dwordx4 v[72:75], v106, s[0:1]
	global_load_dwordx4 v[76:79], v106, s[0:1] offset:1024
	global_load_dwordx4 v[80:83], v106, s[0:1] offset:2048
	global_load_dwordx4 v[84:87], v106, s[0:1] offset:3072
	s_cmp_eq_u32 s42, 0
	s_cbranch_scc1 .LnrmC_loop
	global_load_dwordx4 v[88:91], v106, s[12:13]
	global_load_dwordx4 v[92:95], v106, s[12:13] offset:1024
	global_load_dwordx4 v[96:99], v106, s[12:13] offset:2048
	global_load_dwordx4 v[100:103], v106, s[12:13] offset:3072

.LnrmC_done:
.LBB0_1573:
	v_readlane_b32 s0, v248, 8
	v_readlane_b32 s1, v248, 9
	s_mov_b64 s[12:13], -1
	s_andn2_b64 vcc, exec, s[0:1]
	s_mov_b64 s[0:1], -1
	s_cbranch_vccz .LBB0_1574
	s_getpc_b64 s[98:99]
